# static priority raise for waves 0-3 (older half) instead of 4-7
# speedup vs baseline: 1.0014x; 1.0014x over previous
;     __device__ __forceinline__ bool next(int i, Unit& u) const { Unit t; if (!so.next(i / 3, t)) return false; const int br = i % 3; u.pm = t.pm + br * so.nM; u.pn = t.pn + br * so.nN; return true; }
;     __device__ __forceinline__ bool zero_after(const Unit& u) const { return (u.pn / nN) == 2; }
; template <class Epi, class Sched, bool ALIGN_EPI = false, bool SP2 = false>
; __device__ __forceinline__ void gemm_phase(PG8_LAS unsigned char* lds, const Gemm g, const Sched& S, const Epi& E) {
;     ...
;         const bool has_next = S.next(ui + 1, nxt);
;         const char* nA = has_next ? (const char*)g.A + (size_t)nxt.pm * tstep : cA; const char* nB = has_next ? (const char*)g.Bt + (size_t)nxt.pn * tstep : cB;
;     ...
;         if (E.zero_after(cur)) {
; #pragma unroll
;         for (int a = 0; a < 2; ++a)
; #pragma unroll
;             for (int b = 0; b < 2; ++b)
; #pragma unroll
;                 for (int m = 0; m < 4; ++m)
; #pragma unroll
;                     for (int n = 0; n < 2; ++n) acc[a][b][m][n] = (f32x4){0.f, 0.f, 0.f, 0.f};
;         }
;         cur = nxt; cA = nA; cB = nB; ++ui;
.LBB0_147:
	s_ashr_i32 s25, s24, 31
	s_lshl_b64 s[26:27], s[24:25], 20
	s_add_u32 s26, s1, s26
	s_addc_u32 s27, s40, s27
	s_and_b64 s[28:29], s[4:5], exec
	s_cselect_b32 s25, s27, s7
	s_cselect_b32 s34, s26, s6
	s_ashr_i32 s23, s22, 31
	s_lshl_b64 s[28:29], s[22:23], 20
	s_add_u32 s28, s41, s28
	s_addc_u32 s29, s44, s29
	s_and_b64 s[30:31], s[4:5], exec
	s_cselect_b32 s23, s29, s9
	s_cselect_b32 s35, s28, s8
	s_add_u32 s6, s6, 0x80080
	s_addc_u32 s7, s7, 0
	s_add_u32 s36, s8, 0x100
	s_addc_u32 s37, s9, 0
	s_mov_b32 s38, -2
	v_mov_b64_e32 v[0:1], 0
	v_mov_b64_e32 v[2:3], 0
	v_mov_b64_e32 v[4:5], 0
	v_mov_b64_e32 v[6:7], 0
	v_mov_b64_e32 v[8:9], 0
	v_mov_b64_e32 v[10:11], 0
	v_mov_b64_e32 v[12:13], 0
	v_mov_b64_e32 v[14:15], 0
	v_mov_b64_e32 v[16:17], 0
	v_mov_b64_e32 v[18:19], 0
	v_mov_b64_e32 v[20:21], 0
	v_mov_b64_e32 v[22:23], 0
	v_mov_b64_e32 v[24:25], 0
	v_mov_b64_e32 v[26:27], 0
	v_mov_b64_e32 v[28:29], 0
	v_mov_b64_e32 v[30:31], 0
	v_mov_b64_e32 v[32:33], 0
	v_mov_b64_e32 v[34:35], 0
	v_mov_b64_e32 v[36:37], 0
	v_mov_b64_e32 v[38:39], 0
	v_mov_b64_e32 v[40:41], 0
	v_mov_b64_e32 v[42:43], 0
	v_mov_b64_e32 v[44:45], 0
	v_mov_b64_e32 v[46:47], 0
	v_mov_b64_e32 v[48:49], 0
	v_mov_b64_e32 v[50:51], 0
	v_mov_b64_e32 v[52:53], 0
	v_mov_b64_e32 v[54:55], 0
	v_mov_b64_e32 v[56:57], 0
	v_mov_b64_e32 v[58:59], 0
	v_mov_b64_e32 v[60:61], 0
	v_mov_b64_e32 v[62:63], 0
	v_mov_b64_e32 v[64:65], 0
	v_mov_b64_e32 v[66:67], 0
	v_mov_b64_e32 v[68:69], 0
	v_mov_b64_e32 v[70:71], 0
	v_mov_b64_e32 v[72:73], 0
	v_mov_b64_e32 v[74:75], 0
	v_mov_b64_e32 v[76:77], 0
	v_mov_b64_e32 v[78:79], 0
	v_mov_b64_e32 v[80:81], 0
	v_mov_b64_e32 v[82:83], 0
	v_mov_b64_e32 v[84:85], 0
	v_mov_b64_e32 v[86:87], 0
	v_mov_b64_e32 v[88:89], 0
	v_mov_b64_e32 v[90:91], 0
	v_mov_b64_e32 v[92:93], 0
	v_mov_b64_e32 v[94:95], 0
	v_mov_b64_e32 v[96:97], 0
	v_mov_b64_e32 v[98:99], 0
	v_mov_b64_e32 v[100:101], 0
	v_mov_b64_e32 v[102:103], 0
	v_mov_b64_e32 v[104:105], 0
	v_mov_b64_e32 v[106:107], 0
	v_mov_b64_e32 v[108:109], 0
	v_mov_b64_e32 v[110:111], 0
	v_mov_b64_e32 v[112:113], 0
	v_mov_b64_e32 v[114:115], 0
	v_mov_b64_e32 v[116:117], 0
	v_mov_b64_e32 v[118:119], 0
	v_mov_b64_e32 v[120:121], 0
	v_mov_b64_e32 v[122:123], 0
	v_mov_b64_e32 v[124:125], 0
	v_mov_b64_e32 v[126:127], 0
	s_cmp_eq_u64 s[20:21], 0
	s_cbranch_scc1 .Lprio_skip_148
	s_setprio 1

;     __device__ __forceinline__ bool next(int i, Unit& u) const { Unit t; if (!so.next(i / 3, t)) return false; const int br = i % 3; u.pm = t.pm + br * so.nM; u.pn = t.pn + br * so.nN; return true; }
; template <class Epi, class Sched, bool ALIGN_EPI = false, bool SP2 = false>
; __device__ __forceinline__ void gemm_phase(PG8_LAS unsigned char* lds, const Gemm g, const Sched& S, const Epi& E) {
;     ...
;         const bool has_next = S.next(ui + 1, nxt);
;         const char* nA = has_next ? (const char*)g.A + (size_t)nxt.pm * tstep : cA; const char* nB = has_next ? (const char*)g.Bt + (size_t)nxt.pn * tstep : cB;
;     ...
;         cur = nxt; cA = nA; cB = nB; ++ui;
.LBB0_423:
	s_ashr_i32 s17, s16, 31
	s_lshl_b64 s[20:21], s[16:17], 19
	s_add_u32 s20, s26, s20
	s_addc_u32 s21, s27, s21
	s_and_b64 s[22:23], s[4:5], exec
	s_cselect_b32 s17, s21, s7
	s_cselect_b32 s38, s20, s6
	s_ashr_i32 s19, s18, 31
	s_lshl_b64 s[22:23], s[18:19], 19
	s_add_u32 s22, s28, s22
	s_addc_u32 s23, s29, s23
	s_and_b64 s[24:25], s[4:5], exec
	s_cselect_b32 s19, s23, s9
	s_cselect_b32 s39, s22, s8
	s_add_u32 s6, s6, 0x40080
	s_addc_u32 s7, s7, 0
	s_add_u32 s45, s8, 0x100
	s_addc_u32 s52, s9, 0
	s_mov_b32 s58, -2
	s_cmp_eq_u64 s[14:15], 0
	s_cbranch_scc1 .Lprio_skip_424
	s_setprio 1

;     __device__ __forceinline__ bool next(int i, Unit& u) const { Unit t; if (!so.next(i / 3, t)) return false; const int br = i % 3; u.pm = t.pm + br * so.nM; u.pn = t.pn + br * so.nN; return true; }
;     __device__ __forceinline__ bool zero_after(const Unit& u) const { return (u.pn / nN) == 2; }
; template <class Epi, class Sched, bool ALIGN_EPI = false, bool SP2 = false>
; __device__ __forceinline__ void gemm_phase(PG8_LAS unsigned char* lds, const Gemm g, const Sched& S, const Epi& E) {
;     ...
;         const bool has_next = S.next(ui + 1, nxt);
;         const char* nA = has_next ? (const char*)g.A + (size_t)nxt.pm * tstep : cA; const char* nB = has_next ? (const char*)g.Bt + (size_t)nxt.pn * tstep : cB;
;     ...
;         if (E.zero_after(cur)) {
; #pragma unroll
;         for (int a = 0; a < 2; ++a)
; #pragma unroll
;             for (int b = 0; b < 2; ++b)
; #pragma unroll
;                 for (int m = 0; m < 4; ++m)
; #pragma unroll
;                     for (int n = 0; n < 2; ++n) acc[a][b][m][n] = (f32x4){0.f, 0.f, 0.f, 0.f};
.LBB0_595:
	s_ashr_i32 s19, s18, 31
	s_lshl_b64 s[20:21], s[18:19], 20
	s_add_u32 s20, s2, s20
	s_addc_u32 s21, s30, s21
	s_and_b64 s[22:23], s[8:9], exec
	s_cselect_b32 s19, s21, s25
	s_cselect_b32 s58, s20, s24
	s_ashr_i32 s17, s16, 31
	s_lshl_b64 s[22:23], s[16:17], 20
	s_add_u32 s22, s31, s22
	s_addc_u32 s23, s34, s23
	s_and_b64 s[28:29], s[8:9], exec
	s_cselect_b32 s17, s23, s27
	s_cselect_b32 s62, s22, s26
	s_add_u32 s24, s24, 0x80080
	s_addc_u32 s25, s25, 0
	s_add_u32 s63, s26, 0x100
	v_mov_b32_e32 v0, 0
	s_addc_u32 s66, s27, 0
	s_mov_b32 s67, -2
	v_mov_b32_e32 v1, v0
	v_mov_b32_e32 v2, v0
	v_mov_b32_e32 v3, v0
	v_mov_b32_e32 v4, v0
	v_mov_b32_e32 v5, v0
	v_mov_b32_e32 v6, v0
	v_mov_b32_e32 v7, v0
	v_mov_b32_e32 v16, v0
	v_mov_b32_e32 v17, v0
	v_mov_b32_e32 v18, v0
	v_mov_b32_e32 v19, v0
	v_mov_b32_e32 v20, v0
	v_mov_b32_e32 v21, v0
	v_mov_b32_e32 v22, v0
	v_mov_b32_e32 v23, v0
	v_mov_b32_e32 v32, v0
	v_mov_b32_e32 v33, v0
	v_mov_b32_e32 v34, v0
	v_mov_b32_e32 v35, v0
	v_mov_b32_e32 v36, v0
	v_mov_b32_e32 v37, v0
	v_mov_b32_e32 v38, v0
	v_mov_b32_e32 v39, v0
	v_mov_b32_e32 v48, v0
	v_mov_b32_e32 v49, v0
	v_mov_b32_e32 v50, v0
	v_mov_b32_e32 v51, v0
	v_mov_b32_e32 v52, v0
	v_mov_b32_e32 v53, v0
	v_mov_b32_e32 v54, v0
	v_mov_b32_e32 v55, v0
	v_mov_b32_e32 v8, v0
	v_mov_b32_e32 v9, v0
	v_mov_b32_e32 v10, v0
	v_mov_b32_e32 v11, v0
	v_mov_b32_e32 v12, v0
	v_mov_b32_e32 v13, v0
	v_mov_b32_e32 v14, v0
	v_mov_b32_e32 v15, v0
	v_mov_b32_e32 v24, v0
	v_mov_b32_e32 v25, v0
	v_mov_b32_e32 v26, v0
	v_mov_b32_e32 v27, v0
	v_mov_b32_e32 v28, v0
	v_mov_b32_e32 v29, v0
	v_mov_b32_e32 v30, v0
	v_mov_b32_e32 v31, v0
	v_mov_b32_e32 v40, v0
	v_mov_b32_e32 v41, v0
	v_mov_b32_e32 v42, v0
	v_mov_b32_e32 v43, v0
	v_mov_b32_e32 v44, v0
	v_mov_b32_e32 v45, v0
	v_mov_b32_e32 v46, v0
	v_mov_b32_e32 v47, v0
	v_mov_b32_e32 v56, v0
	v_mov_b32_e32 v57, v0
	v_mov_b32_e32 v58, v0
	v_mov_b32_e32 v59, v0
	v_mov_b32_e32 v60, v0
	v_mov_b32_e32 v61, v0
	v_mov_b32_e32 v62, v0
	v_mov_b32_e32 v63, v0
	v_mov_b32_e32 v64, v0
	v_mov_b32_e32 v65, v0
	v_mov_b32_e32 v66, v0
	v_mov_b32_e32 v67, v0
	v_mov_b32_e32 v68, v0
	v_mov_b32_e32 v69, v0
	v_mov_b32_e32 v70, v0
	v_mov_b32_e32 v71, v0
	v_mov_b32_e32 v80, v0
	v_mov_b32_e32 v81, v0
	v_mov_b32_e32 v82, v0
	v_mov_b32_e32 v83, v0
	v_mov_b32_e32 v84, v0
	v_mov_b32_e32 v85, v0
	v_mov_b32_e32 v86, v0
	v_mov_b32_e32 v87, v0
	v_mov_b32_e32 v96, v0
	v_mov_b32_e32 v97, v0
	v_mov_b32_e32 v98, v0
	v_mov_b32_e32 v99, v0
	v_mov_b32_e32 v100, v0
	v_mov_b32_e32 v101, v0
	v_mov_b32_e32 v102, v0
	v_mov_b32_e32 v103, v0
	v_mov_b32_e32 v128, v0
	v_mov_b32_e32 v129, v0
	v_mov_b32_e32 v130, v0
	v_mov_b32_e32 v131, v0
	v_mov_b32_e32 v136, v0
	v_mov_b32_e32 v137, v0
	v_mov_b32_e32 v138, v0
	v_mov_b32_e32 v139, v0
	v_mov_b32_e32 v72, v0
	v_mov_b32_e32 v73, v0
	v_mov_b32_e32 v74, v0
	v_mov_b32_e32 v75, v0
	v_mov_b32_e32 v76, v0
	v_mov_b32_e32 v77, v0
	v_mov_b32_e32 v78, v0
	v_mov_b32_e32 v79, v0
	v_mov_b32_e32 v88, v0
	v_mov_b32_e32 v89, v0
	v_mov_b32_e32 v90, v0
	v_mov_b32_e32 v91, v0
	v_mov_b32_e32 v92, v0
	v_mov_b32_e32 v93, v0
	v_mov_b32_e32 v94, v0
	v_mov_b32_e32 v95, v0
	v_mov_b32_e32 v104, v0
	v_mov_b32_e32 v105, v0
	v_mov_b32_e32 v106, v0
	v_mov_b32_e32 v107, v0
	v_mov_b32_e32 v108, v0
	v_mov_b32_e32 v109, v0
	v_mov_b32_e32 v110, v0
	v_mov_b32_e32 v111, v0
	v_mov_b32_e32 v152, v0
	v_mov_b32_e32 v153, v0
	v_mov_b32_e32 v154, v0
	v_mov_b32_e32 v155, v0
	v_mov_b32_e32 v160, v0
	v_mov_b32_e32 v161, v0
	v_mov_b32_e32 v162, v0
	v_mov_b32_e32 v163, v0
	s_cmp_eq_u64 s[14:15], 0
	s_cbranch_scc1 .Lprio_skip_596
	s_setprio 1

;     __device__ __forceinline__ bool next(int i, Unit& u) const { Unit t; if (!so.next(i / 3, t)) return false; const int br = i % 3; u.pm = t.pm + br * so.nM; u.pn = t.pn + br * so.nN; return true; }
;     __device__ __forceinline__ bool zero_after(const Unit& u) const { return (u.pn / nN) == 2; }
; template <class Epi, class Sched, bool ALIGN_EPI = false, bool SP2 = false>
; __device__ __forceinline__ void gemm_phase(PG8_LAS unsigned char* lds, const Gemm g, const Sched& S, const Epi& E) {
;     ...
;         const bool has_next = S.next(ui + 1, nxt);
;         const char* nA = has_next ? (const char*)g.A + (size_t)nxt.pm * tstep : cA; const char* nB = has_next ? (const char*)g.Bt + (size_t)nxt.pn * tstep : cB;
;     ...
;         if (E.zero_after(cur)) {
; #pragma unroll
;         for (int a = 0; a < 2; ++a)
; #pragma unroll
;             for (int b = 0; b < 2; ++b)
; #pragma unroll
;                 for (int m = 0; m < 4; ++m)
; #pragma unroll
;                     for (int n = 0; n < 2; ++n) acc[a][b][m][n] = (f32x4){0.f, 0.f, 0.f, 0.f};
.LBB0_683:
	s_ashr_i32 s19, s18, 31
	s_lshl_b64 s[20:21], s[18:19], 20
	s_add_u32 s20, s2, s20
	s_addc_u32 s21, s28, s21
	s_and_b64 s[22:23], s[6:7], exec
	s_cselect_b32 s19, s21, s9
	s_cselect_b32 s45, s20, s8
	s_ashr_i32 s17, s16, 31
	s_lshl_b64 s[22:23], s[16:17], 20
	s_add_u32 s22, s29, s22
	s_addc_u32 s23, s30, s23
	s_and_b64 s[26:27], s[6:7], exec
	s_cselect_b32 s17, s23, s25
	s_cselect_b32 s52, s22, s24
	s_add_u32 s8, s8, 0x80080
	s_addc_u32 s9, s9, 0
	s_add_u32 s58, s24, 0x100
	s_addc_u32 s62, s25, 0
	s_mov_b32 s63, -2
	v_mov_b64_e32 v[0:1], 0
	v_mov_b64_e32 v[2:3], 0
	v_mov_b64_e32 v[4:5], 0
	v_mov_b64_e32 v[6:7], 0
	v_mov_b64_e32 v[8:9], 0
	v_mov_b64_e32 v[10:11], 0
	v_mov_b64_e32 v[12:13], 0
	v_mov_b64_e32 v[14:15], 0
	v_mov_b64_e32 v[16:17], 0
	v_mov_b64_e32 v[18:19], 0
	v_mov_b64_e32 v[20:21], 0
	v_mov_b64_e32 v[22:23], 0
	v_mov_b64_e32 v[24:25], 0
	v_mov_b64_e32 v[26:27], 0
	v_mov_b64_e32 v[28:29], 0
	v_mov_b64_e32 v[30:31], 0
	v_mov_b64_e32 v[32:33], 0
	v_mov_b64_e32 v[34:35], 0
	v_mov_b64_e32 v[36:37], 0
	v_mov_b64_e32 v[38:39], 0
	v_mov_b64_e32 v[40:41], 0
	v_mov_b64_e32 v[42:43], 0
	v_mov_b64_e32 v[44:45], 0
	v_mov_b64_e32 v[46:47], 0
	v_mov_b64_e32 v[48:49], 0
	v_mov_b64_e32 v[50:51], 0
	v_mov_b64_e32 v[52:53], 0
	v_mov_b64_e32 v[54:55], 0
	v_mov_b64_e32 v[56:57], 0
	v_mov_b64_e32 v[58:59], 0
	v_mov_b64_e32 v[60:61], 0
	v_mov_b64_e32 v[62:63], 0
	v_mov_b64_e32 v[64:65], 0
	v_mov_b64_e32 v[66:67], 0
	v_mov_b64_e32 v[68:69], 0
	v_mov_b64_e32 v[70:71], 0
	v_mov_b64_e32 v[72:73], 0
	v_mov_b64_e32 v[74:75], 0
	v_mov_b64_e32 v[76:77], 0
	v_mov_b64_e32 v[78:79], 0
	v_mov_b64_e32 v[80:81], 0
	v_mov_b64_e32 v[82:83], 0
	v_mov_b64_e32 v[84:85], 0
	v_mov_b64_e32 v[86:87], 0
	v_mov_b64_e32 v[88:89], 0
	v_mov_b64_e32 v[90:91], 0
	v_mov_b64_e32 v[92:93], 0
	v_mov_b64_e32 v[94:95], 0
	v_mov_b64_e32 v[96:97], 0
	v_mov_b64_e32 v[98:99], 0
	v_mov_b64_e32 v[100:101], 0
	v_mov_b64_e32 v[102:103], 0
	v_mov_b64_e32 v[104:105], 0
	v_mov_b64_e32 v[106:107], 0
	v_mov_b64_e32 v[108:109], 0
	v_mov_b64_e32 v[110:111], 0
	v_mov_b64_e32 v[112:113], 0
	v_mov_b64_e32 v[114:115], 0
	v_mov_b64_e32 v[116:117], 0
	v_mov_b64_e32 v[118:119], 0
	v_mov_b64_e32 v[120:121], 0
	v_mov_b64_e32 v[122:123], 0
	v_mov_b64_e32 v[124:125], 0
	v_mov_b64_e32 v[126:127], 0
	s_cmp_eq_u64 s[14:15], 0
	s_cbranch_scc1 .Lprio_skip_684
	s_setprio 1

;     __device__ __forceinline__ bool next(int i, Unit& u) const { Unit t; if (!so.next(i / 3, t)) return false; const int br = i % 3; u.pm = t.pm + br * so.nM; u.pn = t.pn + br * so.nN; return true; }
;     __device__ __forceinline__ bool zero_after(const Unit& u) const { return (u.pn / nN) == 2; }
; template <class Epi, class Sched, bool ALIGN_EPI = false, bool SP2 = false>
; __device__ __forceinline__ void gemm_phase(PG8_LAS unsigned char* lds, const Gemm g, const Sched& S, const Epi& E) {
;     ...
;         const bool has_next = S.next(ui + 1, nxt);
;         const char* nA = has_next ? (const char*)g.A + (size_t)nxt.pm * tstep : cA; const char* nB = has_next ? (const char*)g.Bt + (size_t)nxt.pn * tstep : cB;
;     ...
;         if (E.zero_after(cur)) {
; #pragma unroll
;         for (int a = 0; a < 2; ++a)
; #pragma unroll
;             for (int b = 0; b < 2; ++b)
; #pragma unroll
;                 for (int m = 0; m < 4; ++m)
; #pragma unroll
;                     for (int n = 0; n < 2; ++n) acc[a][b][m][n] = (f32x4){0.f, 0.f, 0.f, 0.f};
.LBB0_756:
	s_ashr_i32 s21, s20, 31
	s_lshl_b64 s[22:23], s[20:21], 22
	s_add_u32 s22, s2, s22
	s_addc_u32 s23, s34, s23
	s_and_b64 s[24:25], s[6:7], exec
	s_cselect_b32 s21, s23, s27
	s_cselect_b32 s63, s22, s26
	s_ashr_i32 s19, s18, 31
	s_lshl_b64 s[24:25], s[18:19], 22
	s_add_u32 s24, s35, s24
	s_addc_u32 s25, s36, s25
	s_and_b64 s[30:31], s[6:7], exec
	s_cselect_b32 s19, s25, s29
	s_cselect_b32 s66, s24, s28
	s_add_u32 s26, s26, 0x200080
	s_addc_u32 s27, s27, 0
	s_add_u32 s67, s28, 0x100
	v_mov_b32_e32 v0, 0
	s_addc_u32 s68, s29, 0
	s_mov_b32 s72, -2
	v_mov_b32_e32 v1, v0
	v_mov_b32_e32 v2, v0
	v_mov_b32_e32 v3, v0
	v_mov_b32_e32 v4, v0
	v_mov_b32_e32 v5, v0
	v_mov_b32_e32 v6, v0
	v_mov_b32_e32 v7, v0
	v_mov_b32_e32 v16, v0
	v_mov_b32_e32 v17, v0
	v_mov_b32_e32 v18, v0
	v_mov_b32_e32 v19, v0
	v_mov_b32_e32 v20, v0
	v_mov_b32_e32 v21, v0
	v_mov_b32_e32 v22, v0
	v_mov_b32_e32 v23, v0
	v_mov_b32_e32 v32, v0
	v_mov_b32_e32 v33, v0
	v_mov_b32_e32 v34, v0
	v_mov_b32_e32 v35, v0
	v_mov_b32_e32 v36, v0
	v_mov_b32_e32 v37, v0
	v_mov_b32_e32 v38, v0
	v_mov_b32_e32 v39, v0
	v_mov_b32_e32 v48, v0
	v_mov_b32_e32 v49, v0
	v_mov_b32_e32 v50, v0
	v_mov_b32_e32 v51, v0
	v_mov_b32_e32 v52, v0
	v_mov_b32_e32 v53, v0
	v_mov_b32_e32 v54, v0
	v_mov_b32_e32 v55, v0
	v_mov_b32_e32 v8, v0
	v_mov_b32_e32 v9, v0
	v_mov_b32_e32 v10, v0
	v_mov_b32_e32 v11, v0
	v_mov_b32_e32 v12, v0
	v_mov_b32_e32 v13, v0
	v_mov_b32_e32 v14, v0
	v_mov_b32_e32 v15, v0
	v_mov_b32_e32 v24, v0
	v_mov_b32_e32 v25, v0
	v_mov_b32_e32 v26, v0
	v_mov_b32_e32 v27, v0
	v_mov_b32_e32 v28, v0
	v_mov_b32_e32 v29, v0
	v_mov_b32_e32 v30, v0
	v_mov_b32_e32 v31, v0
	v_mov_b32_e32 v40, v0
	v_mov_b32_e32 v41, v0
	v_mov_b32_e32 v42, v0
	v_mov_b32_e32 v43, v0
	v_mov_b32_e32 v44, v0
	v_mov_b32_e32 v45, v0
	v_mov_b32_e32 v46, v0
	v_mov_b32_e32 v47, v0
	v_mov_b32_e32 v56, v0
	v_mov_b32_e32 v57, v0
	v_mov_b32_e32 v58, v0
	v_mov_b32_e32 v59, v0
	v_mov_b32_e32 v60, v0
	v_mov_b32_e32 v61, v0
	v_mov_b32_e32 v62, v0
	v_mov_b32_e32 v63, v0
	v_mov_b32_e32 v64, v0
	v_mov_b32_e32 v65, v0
	v_mov_b32_e32 v66, v0
	v_mov_b32_e32 v67, v0
	v_mov_b32_e32 v68, v0
	v_mov_b32_e32 v69, v0
	v_mov_b32_e32 v70, v0
	v_mov_b32_e32 v71, v0
	v_mov_b32_e32 v80, v0
	v_mov_b32_e32 v81, v0
	v_mov_b32_e32 v82, v0
	v_mov_b32_e32 v83, v0
	v_mov_b32_e32 v84, v0
	v_mov_b32_e32 v85, v0
	v_mov_b32_e32 v86, v0
	v_mov_b32_e32 v87, v0
	v_mov_b32_e32 v96, v0
	v_mov_b32_e32 v97, v0
	v_mov_b32_e32 v98, v0
	v_mov_b32_e32 v99, v0
	v_mov_b32_e32 v100, v0
	v_mov_b32_e32 v101, v0
	v_mov_b32_e32 v102, v0
	v_mov_b32_e32 v103, v0
	v_mov_b32_e32 v128, v0
	v_mov_b32_e32 v129, v0
	v_mov_b32_e32 v130, v0
	v_mov_b32_e32 v131, v0
	v_mov_b32_e32 v136, v0
	v_mov_b32_e32 v137, v0
	v_mov_b32_e32 v138, v0
	v_mov_b32_e32 v139, v0
	v_mov_b32_e32 v72, v0
	v_mov_b32_e32 v73, v0
	v_mov_b32_e32 v74, v0
	v_mov_b32_e32 v75, v0
	v_mov_b32_e32 v76, v0
	v_mov_b32_e32 v77, v0
	v_mov_b32_e32 v78, v0
	v_mov_b32_e32 v79, v0
	v_mov_b32_e32 v88, v0
	v_mov_b32_e32 v89, v0
	v_mov_b32_e32 v90, v0
	v_mov_b32_e32 v91, v0
	v_mov_b32_e32 v92, v0
	v_mov_b32_e32 v93, v0
	v_mov_b32_e32 v94, v0
	v_mov_b32_e32 v95, v0
	v_mov_b32_e32 v104, v0
	v_mov_b32_e32 v105, v0
	v_mov_b32_e32 v106, v0
	v_mov_b32_e32 v107, v0
	v_mov_b32_e32 v108, v0
	v_mov_b32_e32 v109, v0
	v_mov_b32_e32 v110, v0
	v_mov_b32_e32 v111, v0
	v_mov_b32_e32 v156, v0
	v_mov_b32_e32 v157, v0
	v_mov_b32_e32 v158, v0
	v_mov_b32_e32 v159, v0
	v_mov_b32_e32 v160, v0
	v_mov_b32_e32 v161, v0
	v_mov_b32_e32 v162, v0
	v_mov_b32_e32 v163, v0
	s_cmp_eq_u64 s[16:17], 0
	s_cbranch_scc1 .Lprio_skip_757
	s_setprio 1

;     __device__ __forceinline__ bool next(int i, Unit& u) const { Unit t; if (!so.next(i / 3, t)) return false; const int br = i % 3; u.pm = t.pm + br * so.nM; u.pn = t.pn + br * so.nN; return true; }
; template <class Epi, class Sched, bool ALIGN_EPI = false, bool SP2 = false>
; __device__ __forceinline__ void gemm_phase(PG8_LAS unsigned char* lds, const Gemm g, const Sched& S, const Epi& E) {
;     ...
;     f32x4 acc[2][2][4][2];
; #pragma unroll
;     for (int a = 0; a < 2; ++a)
; #pragma unroll
;         for (int b = 0; b < 2; ++b)
; #pragma unroll
;             for (int m = 0; m < 4; ++m)
; #pragma unroll
;                 for (int n = 0; n < 2; ++n) acc[a][b][m][n] = (f32x4){0.f, 0.f, 0.f, 0.f};
;     ...
;     for (;;) {
;         const bool has_next = S.next(ui + 1, nxt);
;         const char* nA = has_next ? (const char*)g.A + (size_t)nxt.pm * tstep : cA; const char* nB = has_next ? (const char*)g.Bt + (size_t)nxt.pn * tstep : cB;
;         for (int t = 0; t < nt; t += 2) {
.LBB0_849:
	v_mov_b32_e32 v123, 0
	s_andn2_b64 vcc, exec, s[16:17]
	v_mov_b32_e32 v122, v123
	v_mov_b32_e32 v121, v123
	v_mov_b32_e32 v120, v123
	v_mov_b32_e32 v127, v123
	v_mov_b32_e32 v126, v123
	v_mov_b32_e32 v125, v123
	v_mov_b32_e32 v124, v123
	v_mov_b32_e32 v111, v123
	v_mov_b32_e32 v110, v123
	v_mov_b32_e32 v109, v123
	v_mov_b32_e32 v108, v123
	v_mov_b32_e32 v107, v123
	v_mov_b32_e32 v106, v123
	v_mov_b32_e32 v105, v123
	v_mov_b32_e32 v104, v123
	v_mov_b32_e32 v95, v123
	v_mov_b32_e32 v94, v123
	v_mov_b32_e32 v93, v123
	v_mov_b32_e32 v92, v123
	v_mov_b32_e32 v91, v123
	v_mov_b32_e32 v90, v123
	v_mov_b32_e32 v89, v123
	v_mov_b32_e32 v88, v123
	v_mov_b32_e32 v79, v123
	v_mov_b32_e32 v78, v123
	v_mov_b32_e32 v77, v123
	v_mov_b32_e32 v76, v123
	v_mov_b32_e32 v75, v123
	v_mov_b32_e32 v74, v123
	v_mov_b32_e32 v73, v123
	v_mov_b32_e32 v72, v123
	v_mov_b32_e32 v119, v123
	v_mov_b32_e32 v118, v123
	v_mov_b32_e32 v117, v123
	v_mov_b32_e32 v116, v123
	v_mov_b32_e32 v115, v123
	v_mov_b32_e32 v114, v123
	v_mov_b32_e32 v113, v123
	v_mov_b32_e32 v112, v123
	v_mov_b32_e32 v103, v123
	v_mov_b32_e32 v102, v123
	v_mov_b32_e32 v101, v123
	v_mov_b32_e32 v100, v123
	v_mov_b32_e32 v99, v123
	v_mov_b32_e32 v98, v123
	v_mov_b32_e32 v97, v123
	v_mov_b32_e32 v96, v123
	v_mov_b32_e32 v87, v123
	v_mov_b32_e32 v86, v123
	v_mov_b32_e32 v85, v123
	v_mov_b32_e32 v84, v123
	v_mov_b32_e32 v83, v123
	v_mov_b32_e32 v82, v123
	v_mov_b32_e32 v81, v123
	v_mov_b32_e32 v80, v123
	v_mov_b32_e32 v71, v123
	v_mov_b32_e32 v70, v123
	v_mov_b32_e32 v69, v123
	v_mov_b32_e32 v68, v123
	v_mov_b32_e32 v67, v123
	v_mov_b32_e32 v66, v123
	v_mov_b32_e32 v65, v123
	v_mov_b32_e32 v64, v123
	v_mov_b32_e32 v63, v123
	v_mov_b32_e32 v62, v123
	v_mov_b32_e32 v61, v123
	v_mov_b32_e32 v60, v123
	v_mov_b32_e32 v59, v123
	v_mov_b32_e32 v58, v123
	v_mov_b32_e32 v57, v123
	v_mov_b32_e32 v56, v123
	v_mov_b32_e32 v47, v123
	v_mov_b32_e32 v46, v123
	v_mov_b32_e32 v45, v123
	v_mov_b32_e32 v44, v123
	v_mov_b32_e32 v43, v123
	v_mov_b32_e32 v42, v123
	v_mov_b32_e32 v41, v123
	v_mov_b32_e32 v40, v123
	v_mov_b32_e32 v31, v123
	v_mov_b32_e32 v30, v123
	v_mov_b32_e32 v29, v123
	v_mov_b32_e32 v28, v123
	v_mov_b32_e32 v27, v123
	v_mov_b32_e32 v26, v123
	v_mov_b32_e32 v25, v123
	v_mov_b32_e32 v24, v123
	v_mov_b32_e32 v15, v123
	v_mov_b32_e32 v14, v123
	v_mov_b32_e32 v13, v123
	v_mov_b32_e32 v12, v123
	v_mov_b32_e32 v11, v123
	v_mov_b32_e32 v10, v123
	v_mov_b32_e32 v9, v123
	v_mov_b32_e32 v8, v123
	v_mov_b32_e32 v55, v123
	v_mov_b32_e32 v54, v123
	v_mov_b32_e32 v53, v123
	v_mov_b32_e32 v52, v123
	v_mov_b32_e32 v51, v123
	v_mov_b32_e32 v50, v123
	v_mov_b32_e32 v49, v123
	v_mov_b32_e32 v48, v123
	v_mov_b32_e32 v39, v123
	v_mov_b32_e32 v38, v123
	v_mov_b32_e32 v37, v123
	v_mov_b32_e32 v36, v123
	v_mov_b32_e32 v35, v123
	v_mov_b32_e32 v34, v123
	v_mov_b32_e32 v33, v123
	v_mov_b32_e32 v32, v123
	v_mov_b32_e32 v23, v123
	v_mov_b32_e32 v22, v123
	v_mov_b32_e32 v21, v123
	v_mov_b32_e32 v20, v123
	v_mov_b32_e32 v19, v123
	v_mov_b32_e32 v18, v123
	v_mov_b32_e32 v17, v123
	v_mov_b32_e32 v16, v123
	v_mov_b32_e32 v7, v123
	v_mov_b32_e32 v6, v123
	v_mov_b32_e32 v5, v123
	v_mov_b32_e32 v4, v123
	v_mov_b32_e32 v3, v123
	v_mov_b32_e32 v2, v123
	v_mov_b32_e32 v1, v123
	v_mov_b32_e32 v0, v123
	s_cbranch_vccnz .LBB0_853
	s_add_u32 s22, s22, 0x80
	s_addc_u32 s23, s23, 0
	s_add_u32 s58, s24, 0x100
	s_addc_u32 s62, s25, 0
	s_mov_b32 s24, 0
	v_mov_b64_e32 v[0:1], 0
	v_mov_b64_e32 v[2:3], 0
	v_mov_b64_e32 v[4:5], 0
	v_mov_b64_e32 v[6:7], 0
	v_mov_b64_e32 v[8:9], 0
	v_mov_b64_e32 v[10:11], 0
	v_mov_b64_e32 v[12:13], 0
	v_mov_b64_e32 v[14:15], 0
	v_mov_b64_e32 v[16:17], 0
	v_mov_b64_e32 v[18:19], 0
	v_mov_b64_e32 v[20:21], 0
	v_mov_b64_e32 v[22:23], 0
	v_mov_b64_e32 v[24:25], 0
	v_mov_b64_e32 v[26:27], 0
	v_mov_b64_e32 v[28:29], 0
	v_mov_b64_e32 v[30:31], 0
	v_mov_b64_e32 v[32:33], 0
	v_mov_b64_e32 v[34:35], 0
	v_mov_b64_e32 v[36:37], 0
	v_mov_b64_e32 v[38:39], 0
	v_mov_b64_e32 v[40:41], 0
	v_mov_b64_e32 v[42:43], 0
	v_mov_b64_e32 v[44:45], 0
	v_mov_b64_e32 v[46:47], 0
	v_mov_b64_e32 v[48:49], 0
	v_mov_b64_e32 v[50:51], 0
	v_mov_b64_e32 v[52:53], 0
	v_mov_b64_e32 v[54:55], 0
	v_mov_b64_e32 v[56:57], 0
	v_mov_b64_e32 v[58:59], 0
	v_mov_b64_e32 v[60:61], 0
	v_mov_b64_e32 v[62:63], 0
	v_mov_b64_e32 v[64:65], 0
	v_mov_b64_e32 v[66:67], 0
	v_mov_b64_e32 v[68:69], 0
	v_mov_b64_e32 v[70:71], 0
	v_mov_b64_e32 v[72:73], 0
	v_mov_b64_e32 v[74:75], 0
	v_mov_b64_e32 v[76:77], 0
	v_mov_b64_e32 v[78:79], 0
	v_mov_b64_e32 v[80:81], 0
	v_mov_b64_e32 v[82:83], 0
	v_mov_b64_e32 v[84:85], 0
	v_mov_b64_e32 v[86:87], 0
	v_mov_b64_e32 v[88:89], 0
	v_mov_b64_e32 v[90:91], 0
	v_mov_b64_e32 v[92:93], 0
	v_mov_b64_e32 v[94:95], 0
	v_mov_b64_e32 v[96:97], 0
	v_mov_b64_e32 v[98:99], 0
	v_mov_b64_e32 v[100:101], 0
	v_mov_b64_e32 v[102:103], 0
	v_mov_b64_e32 v[104:105], 0
	v_mov_b64_e32 v[106:107], 0
	v_mov_b64_e32 v[108:109], 0
	v_mov_b64_e32 v[110:111], 0
	v_mov_b64_e32 v[112:113], 0
	v_mov_b64_e32 v[114:115], 0
	v_mov_b64_e32 v[116:117], 0
	v_mov_b64_e32 v[118:119], 0
	v_mov_b64_e32 v[120:121], 0
	v_mov_b64_e32 v[122:123], 0
	v_mov_b64_e32 v[124:125], 0
	v_mov_b64_e32 v[126:127], 0
	s_cmp_eq_u64 s[18:19], 0
	s_cbranch_scc1 .Lprio_skip_851
	s_setprio 1

;     __device__ __forceinline__ bool next(int i, Unit& u) const { Unit t; if (!so.next(i / 3, t)) return false; const int br = i % 3; u.pm = t.pm + br * so.nM; u.pn = t.pn + br * so.nN; return true; }
;     __device__ __forceinline__ bool zero_after(const Unit& u) const { return (u.pn / nN) == 2; }
; template <class Epi, class Sched, bool ALIGN_EPI = false, bool SP2 = false>
; __device__ __forceinline__ void gemm_phase(PG8_LAS unsigned char* lds, const Gemm g, const Sched& S, const Epi& E) {
;     ...
;         const bool has_next = S.next(ui + 1, nxt);
;         const char* nA = has_next ? (const char*)g.A + (size_t)nxt.pm * tstep : cA; const char* nB = has_next ? (const char*)g.Bt + (size_t)nxt.pn * tstep : cB;
;     ...
;         if (E.zero_after(cur)) {
; #pragma unroll
;         for (int a = 0; a < 2; ++a)
; #pragma unroll
;             for (int b = 0; b < 2; ++b)
; #pragma unroll
;                 for (int m = 0; m < 4; ++m)
; #pragma unroll
;                     for (int n = 0; n < 2; ++n) acc[a][b][m][n] = (f32x4){0.f, 0.f, 0.f, 0.f};
.LBB0_871:
	s_ashr_i32 s23, s22, 31
	s_lshl_b64 s[24:25], s[22:23], 20
	s_add_u32 s24, s0, s24
	s_addc_u32 s25, s1, s25
	s_and_b64 s[26:27], s[4:5], exec
	s_cselect_b32 s23, s25, s35
	s_cselect_b32 s29, s24, s34
	s_ashr_i32 s21, s20, 31
	s_lshl_b64 s[26:27], s[20:21], 20
	s_add_u32 s26, s40, s26
	s_addc_u32 s27, s41, s27
	s_and_b64 s[38:39], s[4:5], exec
	s_cselect_b32 s21, s27, s37
	s_cselect_b32 s66, s26, s36
	s_add_u32 s34, s34, 0x80080
	s_addc_u32 s35, s35, 0
	s_add_u32 s67, s36, 0x100
	v_mov_b32_e32 v0, 0
	s_addc_u32 s68, s37, 0
	s_mov_b32 s72, -2
	v_mov_b32_e32 v1, v0
	v_mov_b32_e32 v2, v0
	v_mov_b32_e32 v3, v0
	v_mov_b32_e32 v4, v0
	v_mov_b32_e32 v5, v0
	v_mov_b32_e32 v6, v0
	v_mov_b32_e32 v7, v0
	v_mov_b32_e32 v16, v0
	v_mov_b32_e32 v17, v0
	v_mov_b32_e32 v18, v0
	v_mov_b32_e32 v19, v0
	v_mov_b32_e32 v20, v0
	v_mov_b32_e32 v21, v0
	v_mov_b32_e32 v22, v0
	v_mov_b32_e32 v23, v0
	v_mov_b32_e32 v32, v0
	v_mov_b32_e32 v33, v0
	v_mov_b32_e32 v34, v0
	v_mov_b32_e32 v35, v0
	v_mov_b32_e32 v36, v0
	v_mov_b32_e32 v37, v0
	v_mov_b32_e32 v38, v0
	v_mov_b32_e32 v39, v0
	v_mov_b32_e32 v48, v0
	v_mov_b32_e32 v49, v0
	v_mov_b32_e32 v50, v0
	v_mov_b32_e32 v51, v0
	v_mov_b32_e32 v52, v0
	v_mov_b32_e32 v53, v0
	v_mov_b32_e32 v54, v0
	v_mov_b32_e32 v55, v0
	v_mov_b32_e32 v8, v0
	v_mov_b32_e32 v9, v0
	v_mov_b32_e32 v10, v0
	v_mov_b32_e32 v11, v0
	v_mov_b32_e32 v12, v0
	v_mov_b32_e32 v13, v0
	v_mov_b32_e32 v14, v0
	v_mov_b32_e32 v15, v0
	v_mov_b32_e32 v24, v0
	v_mov_b32_e32 v25, v0
	v_mov_b32_e32 v26, v0
	v_mov_b32_e32 v27, v0
	v_mov_b32_e32 v28, v0
	v_mov_b32_e32 v29, v0
	v_mov_b32_e32 v30, v0
	v_mov_b32_e32 v31, v0
	v_mov_b32_e32 v40, v0
	v_mov_b32_e32 v41, v0
	v_mov_b32_e32 v42, v0
	v_mov_b32_e32 v43, v0
	v_mov_b32_e32 v44, v0
	v_mov_b32_e32 v45, v0
	v_mov_b32_e32 v46, v0
	v_mov_b32_e32 v47, v0
	v_mov_b32_e32 v56, v0
	v_mov_b32_e32 v57, v0
	v_mov_b32_e32 v58, v0
	v_mov_b32_e32 v59, v0
	v_mov_b32_e32 v60, v0
	v_mov_b32_e32 v61, v0
	v_mov_b32_e32 v62, v0
	v_mov_b32_e32 v63, v0
	v_mov_b32_e32 v64, v0
	v_mov_b32_e32 v65, v0
	v_mov_b32_e32 v66, v0
	v_mov_b32_e32 v67, v0
	v_mov_b32_e32 v68, v0
	v_mov_b32_e32 v69, v0
	v_mov_b32_e32 v70, v0
	v_mov_b32_e32 v71, v0
	v_mov_b32_e32 v80, v0
	v_mov_b32_e32 v81, v0
	v_mov_b32_e32 v82, v0
	v_mov_b32_e32 v83, v0
	v_mov_b32_e32 v84, v0
	v_mov_b32_e32 v85, v0
	v_mov_b32_e32 v86, v0
	v_mov_b32_e32 v87, v0
	v_mov_b32_e32 v96, v0
	v_mov_b32_e32 v97, v0
	v_mov_b32_e32 v98, v0
	v_mov_b32_e32 v99, v0
	v_mov_b32_e32 v100, v0
	v_mov_b32_e32 v101, v0
	v_mov_b32_e32 v102, v0
	v_mov_b32_e32 v103, v0
	v_mov_b32_e32 v124, v0
	v_mov_b32_e32 v125, v0
	v_mov_b32_e32 v126, v0
	v_mov_b32_e32 v127, v0
	v_mov_b32_e32 v128, v0
	v_mov_b32_e32 v129, v0
	v_mov_b32_e32 v130, v0
	v_mov_b32_e32 v131, v0
	v_mov_b32_e32 v72, v0
	v_mov_b32_e32 v73, v0
	v_mov_b32_e32 v74, v0
	v_mov_b32_e32 v75, v0
	v_mov_b32_e32 v76, v0
	v_mov_b32_e32 v77, v0
	v_mov_b32_e32 v78, v0
	v_mov_b32_e32 v79, v0
	v_mov_b32_e32 v88, v0
	v_mov_b32_e32 v89, v0
	v_mov_b32_e32 v90, v0
	v_mov_b32_e32 v91, v0
	v_mov_b32_e32 v92, v0
	v_mov_b32_e32 v93, v0
	v_mov_b32_e32 v94, v0
	v_mov_b32_e32 v95, v0
	v_mov_b32_e32 v104, v0
	v_mov_b32_e32 v105, v0
	v_mov_b32_e32 v106, v0
	v_mov_b32_e32 v107, v0
	v_mov_b32_e32 v108, v0
	v_mov_b32_e32 v109, v0
	v_mov_b32_e32 v110, v0
	v_mov_b32_e32 v111, v0
	v_mov_b32_e32 v136, v0
	v_mov_b32_e32 v137, v0
	v_mov_b32_e32 v138, v0
	v_mov_b32_e32 v139, v0
	v_mov_b32_e32 v144, v0
	v_mov_b32_e32 v145, v0
	v_mov_b32_e32 v146, v0
	v_mov_b32_e32 v147, v0
	s_cmp_eq_u64 s[18:19], 0
	s_cbranch_scc1 .Lprio_skip_872
	s_setprio 1
